# neighbourhood units: bias-table load no longer waited for on its own; scale + LDS write moved in front of the prologue's last wait so the load overlaps the first K/V DMA and Q loads
# speedup vs baseline: 1.0001x; 1.0001x over previous
.LBB0_595:
	s_mul_hi_i32 s0, s16, 0x2aaaaaab
	s_lshr_b32 s1, s0, 31
	s_ashr_i32 s0, s0, 5
	s_add_i32 s0, s0, s1
	s_mul_i32 s1, s0, 0xc0
	s_sub_i32 s1, s16, s1
	s_and_b32 s6, s1, 31
	s_lshl_b32 s4, s6, 2
	v_sub_u32_e64 v0, s4, 4 clamp
	s_ashr_i32 s5, s1, 5
	v_readfirstlane_b32 s19, v0
	v_med3_u32 v0, s4, 1, v216
	v_mov_b32_e32 v2, v188
	s_movk_i32 s1, 0x1d1
	v_readfirstlane_b32 s7, v0
	s_barrier
	s_nop 0
	v_cmp_gt_i32_e32 vcc, s1, v2
	s_and_saveexec_b64 s[2:3], vcc
	s_cbranch_execz .LBB0_597
	s_load_dwordx2 s[8:9], s[42:43], 0x58
	s_mul_i32 s1, s88, 6
	s_add_i32 s1, s5, s1
	s_mul_hi_i32 s10, s1, 0x744
	s_mulk_i32 s1, 0x744
	s_waitcnt lgkmcnt(0)
	s_add_u32 s8, s8, s1
	v_ashrrev_i32_e32 v3, 31, v2
	s_addc_u32 s9, s9, s10
	v_lshl_add_u64 v[4:5], v[2:3], 2, s[8:9]
	global_load_dword v250, v[4:5], off
	v_lshl_add_u32 v251, v2, 2, 0
	v_add_u32_e32 v251, 0x16000, v251
.LBB0_597:
	s_or_b64 exec, exec, s[2:3]
	s_ashr_i32 s1, s0, 31
	s_lshl_b64 s[2:3], s[0:1], 13
	s_lshl_b32 s1, s6, 8
	s_or_b32 s2, s2, s1
	s_sub_i32 s8, s7, s19
	s_mul_hi_u32 s7, s2, 0xe00
	s_mul_i32 s9, s3, 0xe00
	s_mul_i32 s6, s2, 0xe00
	s_add_i32 s7, s7, s9
	v_readlane_b32 s10, v254, 35
	v_readlane_b32 s11, v254, 36
	s_add_u32 s9, s10, s6
	s_addc_u32 s10, s11, s7
	s_lshl_b32 s6, s5, 6
	s_ashr_i32 s7, s6, 31
	s_lshl_b64 s[36:37], s[6:7], 1
	s_add_u32 s11, s9, s36
	s_addc_u32 s18, s10, s37
	s_add_u32 s6, s12, s36
	s_addc_u32 s7, s13, s37
	s_add_u32 s22, s14, s36
	s_addc_u32 s23, s15, s37
	s_lshl_b32 s9, s0, 8
	s_lshl_b32 s0, s0, 13
	s_lshl_b32 s5, s19, 6
	s_add_i32 s26, s9, 0x4000
	s_or_b32 s10, s5, s0
	v_mov_b32_e32 v14, v191
	s_cmp_eq_u32 s8, 1
	s_waitcnt lgkmcnt(0)
	s_barrier
	s_cselect_b32 s20, 12, 16
	v_readfirstlane_b32 s5, v14
	s_ashr_i32 s17, s5, 6
	v_and_b32_e32 v178, 63, v14
	s_lshl_b32 s44, s17, 5
	s_ashr_i32 s45, s44, 31
	s_mul_i32 s8, s17, 0x1c000
	v_mul_u32_u24_e32 v0, 0x700, v178
	s_mul_hi_i32 s21, s44, 0xe00
	s_add_u32 s24, s11, s8
	v_lshlrev_b32_e32 v0, 1, v0
	s_addc_u32 s25, s18, s21
	v_lshl_add_u64 v[2:3], s[6:7], 0, v[0:1]
	s_lshl_b32 s6, s17, 3
	s_ashr_i32 s7, s6, 31
	v_lshl_add_u64 v[174:175], s[6:7], 1, v[2:3]
	s_lshl_b32 s6, s17, 4
	v_bfe_u32 v0, v14, 2, 4
	v_and_or_b32 v0, s6, 48, v0
	s_ashr_i32 s6, s5, 3
	v_mul_u32_u24_e32 v0, 0x700, v0
	s_andn2_b32 s6, s6, 31
	s_and_b32 s11, s5, 0x3fffffc0
	v_lshlrev_b32_e32 v0, 1, v0
	s_ashr_i32 s7, s6, 31
	v_lshlrev_b32_e32 v179, 3, v14
	s_lshl_b32 s21, s17, 10
	v_lshl_add_u64 v[2:3], s[22:23], 0, v[0:1]
	v_and_b32_e32 v189, 24, v179
	s_cmp_lg_u32 0, -1
	v_lshl_add_u64 v[2:3], s[6:7], 1, v[2:3]
	v_lshlrev_b32_e32 v0, 1, v189
	s_cselect_b32 s6, 0, 0
	v_lshl_add_u64 v[176:177], v[2:3], 0, v[0:1]
	s_add_i32 s21, s21, s6
	v_mad_i64_i32 v[2:3], s[6:7], s26, v217, v[174:175]
	v_and_b32_e32 v180, 31, v14
	v_bfe_u32 v181, v14, 5, 1
	s_mov_b32 s6, m0
	s_mov_b32 m0, s21
	s_nop 0
	global_load_lds_dwordx4 v[2:3], off
	s_mov_b32 m0, s6
	s_add_i32 s22, s21, 0x6000
	v_mad_i64_i32 v[2:3], s[6:7], s26, v217, v[176:177]
	s_mov_b32 s6, m0
	s_mov_b32 m0, s22
	s_nop 0
	global_load_lds_dwordx4 v[2:3], off
	s_mov_b32 m0, s6
	s_add_i32 s7, s9, 0x4040
	v_mul_u32_u24_e32 v0, 0x700, v180
	v_lshlrev_b32_e32 v193, 4, v181
	v_mad_i64_i32 v[2:3], s[26:27], s7, v217, v[174:175]
	s_add_i32 s6, s21, 0x2000
	s_mov_b32 s8, m0
	s_mov_b32 m0, s6
	s_nop 0
	global_load_lds_dwordx4 v[2:3], off
	s_mov_b32 m0, s8
	v_lshl_or_b32 v0, v0, 1, v193
	global_load_dwordx4 v[126:129], v0, s[24:25] offset:1280
	global_load_dwordx4 v[118:121], v0, s[24:25] offset:1312
	global_load_dwordx4 v[106:109], v0, s[24:25] offset:1344
	global_load_dwordx4 v[98:101], v0, s[24:25] offset:1376
	v_lshlrev_b32_e32 v0, 10, v181
	v_lshlrev_b32_e32 v2, 4, v180
	s_add_i32 s8, s9, 0x4080
	v_add3_u32 v197, 0, v0, v2
	v_mad_i64_i32 v[2:3], s[24:25], s8, v217, v[174:175]
	s_add_i32 s6, s21, 0x4000
	s_mov_b32 s18, m0
	s_mov_b32 m0, s6
	s_nop 0
	global_load_lds_dwordx4 v[2:3], off
	s_mov_b32 m0, s18
	s_waitcnt vmcnt(8)
	s_movk_i32 vcc_lo, 0x1d1
	v_cmp_gt_i32_e32 vcc, vcc_lo, v14
	s_and_b64 exec, exec, vcc
	v_mul_f32_e32 v250, 0x3fb8aa3b, v250
	ds_write_b32 v251, v250
	s_mov_b64 exec, -1
	s_waitcnt vmcnt(3) lgkmcnt(0)
	s_barrier
	ds_read_b128 v[2:5], v197
	ds_read_b128 v[6:9], v197 offset:512
	s_addk_i32 s9, 0x40c0
	s_lshl_b32 s11, s11, 2
	s_add_i32 s18, s11, 0
	v_lshlrev_b32_e32 v0, 1, v14
	s_mov_b32 s56, 0
	v_and_b32_e32 v192, 32, v0
	s_mov_b32 s57, s56
	v_add_u32_e32 v54, 0, v192
	s_ashr_i32 s5, s5, 7
	s_mov_b32 s58, s56
	s_mov_b32 s59, s56
	s_mov_b32 s60, s56
	s_mov_b32 s61, s56
	s_mov_b32 s62, s56
	s_waitcnt vmcnt(3) lgkmcnt(1)
	v_mfma_f32_32x32x16_bf16 v[34:49], v[2:5], v[126:129], 0
	s_mov_b32 s63, s56
	s_mov_b32 s64, s56
	s_mov_b32 s65, s56
	s_mov_b32 s66, s56
	s_mov_b32 s67, s56
	s_mov_b32 s68, s56
	s_mov_b32 s69, s56
	s_waitcnt lgkmcnt(0)
	v_mfma_f32_32x32x16_bf16 v[18:33], v[6:9], v[126:129], 0
	ds_read_b128 v[2:5], v197 offset:2048
	ds_read_b128 v[6:9], v197 offset:2560
	s_mov_b32 s70, s56
	s_mov_b32 s71, s56
	s_or_b32 s0, s0, s1
	s_mov_b32 s23, 1
	s_movk_i32 s6, 0x4000
	s_mov_b32 s38, -1
	s_waitcnt vmcnt(2) lgkmcnt(1)
	v_mfma_f32_32x32x16_bf16 v[34:49], v[2:5], v[118:121], v[34:49]
	ds_read_b128 v[2:5], v197 offset:4608
	ds_read_b128 v[10:13], v197 offset:4096
	s_movk_i32 s35, 0x2000
	v_and_or_b32 v198, s44, 32, v180
	v_cmp_gt_u32_e64 s[40:41], 32, v178
	v_lshl_add_u32 v194, v180, 2, s18
	v_mov_b32_e32 v200, 0
	s_mov_b32 s33, 64
	s_waitcnt lgkmcnt(2)
	v_mfma_f32_32x32x16_bf16 v[18:33], v[6:9], v[118:121], v[18:33]
	ds_read_b128 v[50:53], v197 offset:6656
	ds_read_b128 v[6:9], v197 offset:6144
	s_waitcnt vmcnt(1) lgkmcnt(2)
	v_mfma_f32_32x32x16_bf16 v[34:49], v[10:13], v[106:109], v[34:49]
	v_mfma_f32_32x32x16_bf16 v[18:33], v[2:5], v[106:109], v[18:33]
	v_lshlrev_b32_e32 v2, 4, v14
	v_and_b32_e32 v0, 0xc0, v2
	v_lshl_or_b32 v0, v181, 8, v0
	v_add3_u32 v195, v54, v189, v0
	s_waitcnt vmcnt(0) lgkmcnt(0)
	v_mfma_f32_32x32x16_bf16 v[34:49], v[6:9], v[98:101], v[34:49]
	v_mov_b64_e32 v[2:3], s[56:57]
	v_mov_b64_e32 v[16:17], s[70:71]
	v_mov_b64_e32 v[4:5], s[58:59]
	v_mov_b64_e32 v[6:7], s[60:61]
	v_mov_b64_e32 v[8:9], s[62:63]
	v_mov_b64_e32 v[10:11], s[64:65]
	v_mov_b64_e32 v[12:13], s[66:67]
	v_mfma_f32_32x32x16_bf16 v[18:33], v[50:53], v[98:101], v[18:33]
	s_nop 15
	s_nop 7
	s_waitcnt vmcnt(0) lgkmcnt(0)
	s_barrier
	v_mov_b64_e32 v[14:15], s[68:69]
	v_max3_f32 v50, v34, v35, v18
	v_max3_f32 v51, v36, v37, v19
	s_nop 0
	v_max3_f32 v50, v50, v20, v21
	v_max3_f32 v51, v51, v40, v41
	s_nop 0
	v_max3_f32 v50, v50, v38, v39
	v_max3_f32 v51, v51, v24, v25
	s_nop 0
	v_max3_f32 v50, v50, v22, v23
	v_max3_f32 v51, v51, v44, v45
	s_nop 0
	v_max3_f32 v50, v50, v42, v43
	v_max3_f32 v51, v51, v28, v29
	s_nop 0
	v_max3_f32 v50, v50, v26, v27
	v_max3_f32 v51, v51, v48, v49
	s_nop 0
	v_max3_f32 v50, v50, v46, v47
	v_max3_f32 v51, v51, v32, v33
	s_nop 0
	v_max3_f32 v50, v50, v30, v31
	s_nop 0
	v_max_f32_e32 v50, v50, v51
	s_nop 0
	v_mov_b32_e32 v51, v50
	s_nop 1
	v_permlane32_swap_b32_e32 v50, v51
	v_max_f32_e32 v50, v50, v51
	s_nop 0
	v_sub_f32_e32 v66, v18, v50
	v_sub_f32_e32 v67, v19, v50
	v_mad_i64_i32 v[18:19], s[24:25], s9, v217, v[174:175]
	s_mov_b32 s9, m0
	s_mov_b32 m0, s21
	s_nop 0
	global_load_lds_dwordx4 v[18:19], off
	s_mov_b32 m0, s9
	v_mad_i64_i32 v[18:19], s[24:25], s7, v217, v[176:177]
	s_add_i32 s9, s21, 0x8000
	s_mov_b32 s11, m0
	s_mov_b32 m0, s9
	s_nop 0
	global_load_lds_dwordx4 v[18:19], off
	s_mov_b32 m0, s11
	ds_read_b128 v[158:161], v197 offset:8192
	ds_read_b128 v[154:157], v197 offset:8704
	ds_read_b128 v[150:153], v197 offset:10240
	ds_read_b128 v[146:149], v197 offset:10752
	ds_read_b128 v[142:145], v197 offset:12288
	ds_read_b128 v[138:141], v197 offset:12800
	ds_read_b128 v[134:137], v197 offset:14336
	ds_read_b128 v[130:133], v197 offset:14848
	v_sub_f32_e32 v34, v34, v50
	v_sub_f32_e32 v35, v35, v50
	v_sub_f32_e32 v36, v36, v50
	v_sub_f32_e32 v37, v37, v50
	v_sub_f32_e32 v38, v38, v50
	v_sub_f32_e32 v39, v39, v50
	v_sub_f32_e32 v40, v40, v50
	v_sub_f32_e32 v41, v41, v50
	v_sub_f32_e32 v42, v42, v50
	v_sub_f32_e32 v43, v43, v50
	v_sub_f32_e32 v44, v44, v50
	v_sub_f32_e32 v45, v45, v50
	v_sub_f32_e32 v46, v46, v50
	v_sub_f32_e32 v47, v47, v50
	v_sub_f32_e32 v48, v48, v50
	v_sub_f32_e32 v49, v49, v50
	v_add_f32_e32 v196, v1, v50
	v_sub_f32_e32 v20, v20, v50
	v_sub_f32_e32 v21, v21, v50
	v_sub_f32_e32 v22, v22, v50
	v_sub_f32_e32 v23, v23, v50
	v_sub_f32_e32 v24, v24, v50
	v_sub_f32_e32 v25, v25, v50
	v_sub_f32_e32 v26, v26, v50
	v_sub_f32_e32 v27, v27, v50
	v_sub_f32_e32 v28, v28, v50
	v_sub_f32_e32 v29, v29, v50
	v_sub_f32_e32 v30, v30, v50
	v_sub_f32_e32 v31, v31, v50
	v_sub_f32_e32 v32, v32, v50
	v_sub_f32_e32 v33, v33, v50
	s_nop 0
	v_exp_f32_e32 v65, v49
	v_exp_f32_e32 v50, v34
	v_exp_f32_e32 v51, v35
	v_exp_f32_e32 v52, v36
	v_exp_f32_e32 v53, v37
	v_exp_f32_e32 v54, v38
	v_exp_f32_e32 v55, v39
	v_exp_f32_e32 v56, v40
	v_exp_f32_e32 v57, v41
	v_exp_f32_e32 v58, v42
	v_exp_f32_e32 v59, v43
	v_exp_f32_e32 v60, v44
	v_exp_f32_e32 v61, v45
	v_exp_f32_e32 v62, v46
	v_exp_f32_e32 v63, v47
	v_exp_f32_e32 v64, v48
	v_exp_f32_e32 v49, v33
	v_exp_f32_e32 v34, v66
	v_exp_f32_e32 v35, v67
	v_exp_f32_e32 v36, v20
	v_exp_f32_e32 v37, v21
	v_exp_f32_e32 v38, v22
	v_exp_f32_e32 v39, v23
	v_exp_f32_e32 v40, v24
	v_exp_f32_e32 v41, v25
	v_exp_f32_e32 v42, v26
	v_exp_f32_e32 v43, v27
	v_exp_f32_e32 v44, v28
	v_exp_f32_e32 v45, v29
	v_exp_f32_e32 v46, v30
	v_exp_f32_e32 v47, v31
	v_exp_f32_e32 v48, v32
	s_add_i32 s24, s5, s4
	s_min_u32 s4, s4, 4
	s_waitcnt vmcnt(2) lgkmcnt(0)
	s_barrier
	v_med3_i32 v199, s24, 4, v218
	s_add_i32 s5, s5, s4
	s_lshl_b32 s1, s4, 6
	v_readfirstlane_b32 s9, v199
	s_mul_i32 s5, s5, 31
	s_sub_i32 s31, s0, s1
	s_bitset1_b32 s0, 7
	v_mov_b64_e32 v[32:33], v[16:17]
	s_add_i32 s25, s20, -5
	s_sub_i32 s26, s19, s9
	s_add_i32 s9, s10, 0xffffff40
	s_addk_i32 s10, 0xff80
	s_sub_i32 s11, 0xe5, s5
	s_sub_i32 s28, s0, s1
	s_sub_i32 s27, 0xc9, s5
	v_mov_b64_e32 v[30:31], v[14:15]
	v_mov_b64_e32 v[28:29], v[12:13]
	v_mov_b64_e32 v[26:27], v[10:11]
	v_mov_b64_e32 v[24:25], v[8:9]
	v_mov_b64_e32 v[22:23], v[6:7]
	v_mov_b64_e32 v[20:21], v[4:5]
	v_mov_b64_e32 v[18:19], v[2:3]
